# NSA top-k radix select: two queries interleaved per iteration (second chain on s98-s101) to hide the compare-to-popcount latency
# speedup vs baseline: 1.0036x; 1.0036x over previous
.LBB0_547:
	s_and_b64 vcc, exec, s[22:23]
	s_cbranch_vccz .Ltk1_cold
	ds_read_b32 v36, v37
	ds_read_b32 v222, v37 offset:256
	s_waitcnt lgkmcnt(0)
	v_max_f32_e32 v36, v36, v36
	v_max_f32_e32 v36, 0, v36
	v_add_u32_e32 v36, 1, v36
	v_cndmask_b32_e64 v36, v251, v36, s[10:11]
	v_cndmask_b32_e64 v36, 0, v36, s[6:7]
	v_max_f32_e32 v222, v222, v222
	v_max_f32_e32 v222, 0, v222
	v_add_u32_e32 v222, 1, v222
	v_cndmask_b32_e64 v222, v251, v222, s[10:11]
	v_cndmask_b32_e64 v222, 0, v222, s[6:7]
	v_cmp_lt_u32_e32 vcc, s3, v36
	v_cmp_lt_u32_e64 s[100:101], s3, v222
	s_bcnt1_i32_b64 s74, vcc
	s_bcnt1_i32_b64 s100, s[100:101]
	s_cmp_gt_u32 s74, 15
	s_cselect_b32 s14, 2.0, 0
	s_cmp_gt_u32 s100, 15
	s_cselect_b32 s98, 2.0, 0
	s_or_b32 s15, s14, 0x20000000
	s_or_b32 s99, s98, 0x20000000
	v_cmp_le_u32_e32 vcc, s15, v36
	v_cmp_le_u32_e64 s[100:101], s99, v222
	s_bcnt1_i32_b64 s74, vcc
	s_bcnt1_i32_b64 s100, s[100:101]
	s_cmp_gt_u32 s74, 15
	s_cselect_b32 s14, s15, s14
	s_cmp_gt_u32 s100, 15
	s_cselect_b32 s98, s99, s98
	s_or_b32 s15, s14, 0x10000000
	s_or_b32 s99, s98, 0x10000000
	v_cmp_le_u32_e32 vcc, s15, v36
	v_cmp_le_u32_e64 s[100:101], s99, v222
	s_bcnt1_i32_b64 s74, vcc
	s_bcnt1_i32_b64 s100, s[100:101]
	s_cmp_gt_u32 s74, 15
	s_cselect_b32 s14, s15, s14
	s_cmp_gt_u32 s100, 15
	s_cselect_b32 s98, s99, s98
	s_or_b32 s15, s14, 0x8000000
	s_or_b32 s99, s98, 0x8000000
	v_cmp_le_u32_e32 vcc, s15, v36
	v_cmp_le_u32_e64 s[100:101], s99, v222
	s_bcnt1_i32_b64 s74, vcc
	s_bcnt1_i32_b64 s100, s[100:101]
	s_cmp_gt_u32 s74, 15
	s_cselect_b32 s14, s15, s14
	s_cmp_gt_u32 s100, 15
	s_cselect_b32 s98, s99, s98
	s_or_b32 s15, s14, 0x4000000
	s_or_b32 s99, s98, 0x4000000
	v_cmp_le_u32_e32 vcc, s15, v36
	v_cmp_le_u32_e64 s[100:101], s99, v222
	s_bcnt1_i32_b64 s74, vcc
	s_bcnt1_i32_b64 s100, s[100:101]
	s_cmp_gt_u32 s74, 15
	s_cselect_b32 s14, s15, s14
	s_cmp_gt_u32 s100, 15
	s_cselect_b32 s98, s99, s98
	s_or_b32 s15, s14, 0x2000000
	s_or_b32 s99, s98, 0x2000000
	v_cmp_le_u32_e32 vcc, s15, v36
	v_cmp_le_u32_e64 s[100:101], s99, v222
	s_bcnt1_i32_b64 s74, vcc
	s_bcnt1_i32_b64 s100, s[100:101]
	s_cmp_gt_u32 s74, 15
	s_cselect_b32 s14, s15, s14
	s_cmp_gt_u32 s100, 15
	s_cselect_b32 s98, s99, s98
	s_or_b32 s15, s14, 0x1000000
	s_or_b32 s99, s98, 0x1000000
	v_cmp_le_u32_e32 vcc, s15, v36
	v_cmp_le_u32_e64 s[100:101], s99, v222
	s_bcnt1_i32_b64 s74, vcc
	s_bcnt1_i32_b64 s100, s[100:101]
	s_cmp_gt_u32 s74, 15
	s_cselect_b32 s14, s15, s14
	s_cmp_gt_u32 s100, 15
	s_cselect_b32 s98, s99, s98
	s_or_b32 s15, s14, 0x800000
	s_or_b32 s99, s98, 0x800000
	v_cmp_le_u32_e32 vcc, s15, v36
	v_cmp_le_u32_e64 s[100:101], s99, v222
	s_bcnt1_i32_b64 s74, vcc
	s_bcnt1_i32_b64 s100, s[100:101]
	s_cmp_gt_u32 s74, 15
	s_cselect_b32 s14, s15, s14
	s_cmp_gt_u32 s100, 15
	s_cselect_b32 s98, s99, s98
	s_or_b32 s15, s14, 0x400000
	s_or_b32 s99, s98, 0x400000
	v_cmp_le_u32_e32 vcc, s15, v36
	v_cmp_le_u32_e64 s[100:101], s99, v222
	s_bcnt1_i32_b64 s74, vcc
	s_bcnt1_i32_b64 s100, s[100:101]
	s_cmp_gt_u32 s74, 15
	s_cselect_b32 s14, s15, s14
	s_cmp_gt_u32 s100, 15
	s_cselect_b32 s98, s99, s98
	s_or_b32 s15, s14, 0x200000
	s_or_b32 s99, s98, 0x200000
	v_cmp_le_u32_e32 vcc, s15, v36
	v_cmp_le_u32_e64 s[100:101], s99, v222
	s_bcnt1_i32_b64 s74, vcc
	s_bcnt1_i32_b64 s100, s[100:101]
	s_cmp_gt_u32 s74, 15
	s_cselect_b32 s14, s15, s14
	s_cmp_gt_u32 s100, 15
	s_cselect_b32 s98, s99, s98
	s_or_b32 s15, s14, 0x100000
	s_or_b32 s99, s98, 0x100000
	v_cmp_le_u32_e32 vcc, s15, v36
	v_cmp_le_u32_e64 s[100:101], s99, v222
	s_bcnt1_i32_b64 s74, vcc
	s_bcnt1_i32_b64 s100, s[100:101]
	s_cmp_gt_u32 s74, 15
	s_cselect_b32 s14, s15, s14
	s_cmp_gt_u32 s100, 15
	s_cselect_b32 s98, s99, s98
	s_or_b32 s15, s14, 0x80000
	s_or_b32 s99, s98, 0x80000
	v_cmp_le_u32_e32 vcc, s15, v36
	v_cmp_le_u32_e64 s[100:101], s99, v222
	s_bcnt1_i32_b64 s74, vcc
	s_bcnt1_i32_b64 s100, s[100:101]
	s_cmp_gt_u32 s74, 15
	s_cselect_b32 s14, s15, s14
	s_cmp_gt_u32 s100, 15
	s_cselect_b32 s98, s99, s98
	s_or_b32 s15, s14, 0x40000
	s_or_b32 s99, s98, 0x40000
	v_cmp_le_u32_e32 vcc, s15, v36
	v_cmp_le_u32_e64 s[100:101], s99, v222
	s_bcnt1_i32_b64 s74, vcc
	s_bcnt1_i32_b64 s100, s[100:101]
	s_cmp_gt_u32 s74, 15
	s_cselect_b32 s14, s15, s14
	s_cmp_gt_u32 s100, 15
	s_cselect_b32 s98, s99, s98
	s_or_b32 s15, s14, 0x20000
	s_or_b32 s99, s98, 0x20000
	v_cmp_le_u32_e32 vcc, s15, v36
	v_cmp_le_u32_e64 s[100:101], s99, v222
	s_bcnt1_i32_b64 s74, vcc
	s_bcnt1_i32_b64 s100, s[100:101]
	s_cmp_gt_u32 s74, 15
	s_cselect_b32 s14, s15, s14
	s_cmp_gt_u32 s100, 15
	s_cselect_b32 s98, s99, s98
	s_or_b32 s15, s14, 0x10000
	s_or_b32 s99, s98, 0x10000
	v_cmp_le_u32_e32 vcc, s15, v36
	v_cmp_le_u32_e64 s[100:101], s99, v222
	s_bcnt1_i32_b64 s74, vcc
	s_bcnt1_i32_b64 s100, s[100:101]
	s_cmp_gt_u32 s74, 15
	s_cselect_b32 s14, s15, s14
	s_cmp_gt_u32 s100, 15
	s_cselect_b32 s98, s99, s98
	s_or_b32 s15, s14, 0x8000
	s_or_b32 s99, s98, 0x8000
	v_cmp_le_u32_e32 vcc, s15, v36
	v_cmp_le_u32_e64 s[100:101], s99, v222
	s_bcnt1_i32_b64 s74, vcc
	s_bcnt1_i32_b64 s100, s[100:101]
	s_cmp_gt_u32 s74, 15
	s_cselect_b32 s14, s15, s14
	s_cmp_gt_u32 s100, 15
	s_cselect_b32 s98, s99, s98
	s_or_b32 s15, s14, 0x4000
	s_or_b32 s99, s98, 0x4000
	v_cmp_le_u32_e32 vcc, s15, v36
	v_cmp_le_u32_e64 s[100:101], s99, v222
	s_bcnt1_i32_b64 s74, vcc
	s_bcnt1_i32_b64 s100, s[100:101]
	s_cmp_gt_u32 s74, 15
	s_cselect_b32 s14, s15, s14
	s_cmp_gt_u32 s100, 15
	s_cselect_b32 s98, s99, s98
	s_or_b32 s15, s14, 0x2000
	s_or_b32 s99, s98, 0x2000
	v_cmp_le_u32_e32 vcc, s15, v36
	v_cmp_le_u32_e64 s[100:101], s99, v222
	s_bcnt1_i32_b64 s74, vcc
	s_bcnt1_i32_b64 s100, s[100:101]
	s_cmp_gt_u32 s74, 15
	s_cselect_b32 s14, s15, s14
	s_cmp_gt_u32 s100, 15
	s_cselect_b32 s98, s99, s98
	s_or_b32 s15, s14, 0x1000
	s_or_b32 s99, s98, 0x1000
	v_cmp_le_u32_e32 vcc, s15, v36
	v_cmp_le_u32_e64 s[100:101], s99, v222
	s_bcnt1_i32_b64 s74, vcc
	s_bcnt1_i32_b64 s100, s[100:101]
	s_cmp_gt_u32 s74, 15
	s_cselect_b32 s14, s15, s14
	s_cmp_gt_u32 s100, 15
	s_cselect_b32 s98, s99, s98
	s_or_b32 s15, s14, 0x800
	s_or_b32 s99, s98, 0x800
	v_cmp_le_u32_e32 vcc, s15, v36
	v_cmp_le_u32_e64 s[100:101], s99, v222
	s_bcnt1_i32_b64 s74, vcc
	s_bcnt1_i32_b64 s100, s[100:101]
	s_cmp_gt_u32 s74, 15
	s_cselect_b32 s14, s15, s14
	s_cmp_gt_u32 s100, 15
	s_cselect_b32 s98, s99, s98
	s_or_b32 s15, s14, 0x400
	s_or_b32 s99, s98, 0x400
	v_cmp_le_u32_e32 vcc, s15, v36
	v_cmp_le_u32_e64 s[100:101], s99, v222
	s_bcnt1_i32_b64 s74, vcc
	s_bcnt1_i32_b64 s100, s[100:101]
	s_cmp_gt_u32 s74, 15
	s_cselect_b32 s14, s15, s14
	s_cmp_gt_u32 s100, 15
	s_cselect_b32 s98, s99, s98
	s_or_b32 s15, s14, 0x200
	s_or_b32 s99, s98, 0x200
	v_cmp_le_u32_e32 vcc, s15, v36
	v_cmp_le_u32_e64 s[100:101], s99, v222
	s_bcnt1_i32_b64 s74, vcc
	s_bcnt1_i32_b64 s100, s[100:101]
	s_cmp_gt_u32 s74, 15
	s_cselect_b32 s14, s15, s14
	s_cmp_gt_u32 s100, 15
	s_cselect_b32 s98, s99, s98
	s_or_b32 s15, s14, 0x100
	s_or_b32 s99, s98, 0x100
	v_cmp_le_u32_e32 vcc, s15, v36
	v_cmp_le_u32_e64 s[100:101], s99, v222
	s_bcnt1_i32_b64 s74, vcc
	s_bcnt1_i32_b64 s100, s[100:101]
	s_cmp_gt_u32 s74, 15
	s_cselect_b32 s14, s15, s14
	s_cmp_gt_u32 s100, 15
	s_cselect_b32 s98, s99, s98
	s_or_b32 s15, s14, 0x80
	s_or_b32 s99, s98, 0x80
	v_cmp_le_u32_e32 vcc, s15, v36
	v_cmp_le_u32_e64 s[100:101], s99, v222
	s_bcnt1_i32_b64 s74, vcc
	s_bcnt1_i32_b64 s100, s[100:101]
	s_cmp_gt_u32 s74, 15
	s_cselect_b32 s14, s15, s14
	s_cmp_gt_u32 s100, 15
	s_cselect_b32 s98, s99, s98
	s_or_b32 s15, s14, 64
	s_or_b32 s99, s98, 64
	v_cmp_le_u32_e32 vcc, s15, v36
	v_cmp_le_u32_e64 s[100:101], s99, v222
	s_bcnt1_i32_b64 s74, vcc
	s_bcnt1_i32_b64 s100, s[100:101]
	s_cmp_gt_u32 s74, 15
	s_cselect_b32 s14, s15, s14
	s_cmp_gt_u32 s100, 15
	s_cselect_b32 s98, s99, s98
	s_or_b32 s15, s14, 32
	s_or_b32 s99, s98, 32
	v_cmp_le_u32_e32 vcc, s15, v36
	v_cmp_le_u32_e64 s[100:101], s99, v222
	s_bcnt1_i32_b64 s74, vcc
	s_bcnt1_i32_b64 s100, s[100:101]
	s_cmp_gt_u32 s74, 15
	s_cselect_b32 s14, s15, s14
	s_cmp_gt_u32 s100, 15
	s_cselect_b32 s98, s99, s98
	s_or_b32 s15, s14, 16
	s_or_b32 s99, s98, 16
	v_cmp_le_u32_e32 vcc, s15, v36
	v_cmp_le_u32_e64 s[100:101], s99, v222
	s_bcnt1_i32_b64 s74, vcc
	s_bcnt1_i32_b64 s100, s[100:101]
	s_cmp_gt_u32 s74, 15
	s_cselect_b32 s14, s15, s14
	s_cmp_gt_u32 s100, 15
	s_cselect_b32 s98, s99, s98
	s_or_b32 s15, s14, 8
	s_or_b32 s99, s98, 8
	v_cmp_le_u32_e32 vcc, s15, v36
	v_cmp_le_u32_e64 s[100:101], s99, v222
	s_bcnt1_i32_b64 s74, vcc
	s_bcnt1_i32_b64 s100, s[100:101]
	s_cmp_gt_u32 s74, 15
	s_cselect_b32 s14, s15, s14
	s_cmp_gt_u32 s100, 15
	s_cselect_b32 s98, s99, s98
	s_or_b32 s15, s14, 4
	s_or_b32 s99, s98, 4
	v_cmp_le_u32_e32 vcc, s15, v36
	v_cmp_le_u32_e64 s[100:101], s99, v222
	s_bcnt1_i32_b64 s74, vcc
	s_bcnt1_i32_b64 s100, s[100:101]
	s_cmp_gt_u32 s74, 15
	s_cselect_b32 s14, s15, s14
	s_cmp_gt_u32 s100, 15
	s_cselect_b32 s98, s99, s98
	s_or_b32 s15, s14, 2
	s_or_b32 s99, s98, 2
	v_cmp_le_u32_e32 vcc, s15, v36
	v_cmp_le_u32_e64 s[100:101], s99, v222
	s_bcnt1_i32_b64 s74, vcc
	s_bcnt1_i32_b64 s100, s[100:101]
	s_cmp_gt_u32 s74, 15
	s_cselect_b32 s14, s15, s14
	s_cmp_gt_u32 s100, 15
	s_cselect_b32 s98, s99, s98
	s_or_b32 s15, s14, 1
	s_or_b32 s99, s98, 1
	v_cmp_le_u32_e32 vcc, s15, v36
	v_cmp_le_u32_e64 s[100:101], s99, v222
	s_bcnt1_i32_b64 s74, vcc
	s_bcnt1_i32_b64 s100, s[100:101]
	s_cmp_gt_u32 s74, 15
	s_cselect_b32 s12, s15, s14
	s_cmp_gt_u32 s100, 15
	s_cselect_b32 s98, s99, s98
	v_cmp_lt_u32_e32 vcc, s12, v36
	v_cmp_eq_u32_e64 s[12:13], s12, v36
	s_bcnt1_i32_b64 s14, vcc
	s_sub_i32 s14, 16, s14
	v_and_b32_e32 v36, s12, v0
	v_and_b32_e32 v39, s13, v35
	v_bcnt_u32_b32 v36, v36, 0
	v_bcnt_u32_b32 v36, v39, v36
	v_cmp_gt_i32_e64 s[14:15], s14, v36
	s_and_b64 s[12:13], s[12:13], s[14:15]
	s_or_b64 s[12:13], vcc, s[12:13]
	v_cndmask_b32_e64 v36, 0, 1, s[12:13]
	v_cmp_ne_u32_e64 s[12:13], 0, v36
	v_cmp_lt_u32_e32 vcc, s98, v222
	v_cmp_eq_u32_e64 s[100:101], s98, v222
	s_bcnt1_i32_b64 s99, vcc
	s_sub_i32 s99, 16, s99
	v_and_b32_e32 v222, s100, v0
	v_and_b32_e32 v223, s101, v35
	v_bcnt_u32_b32 v222, v222, 0
	v_bcnt_u32_b32 v222, v223, v222
	v_cmp_gt_i32_e64 s[14:15], s99, v222
	s_and_b64 s[100:101], s[100:101], s[14:15]
	s_or_b64 s[100:101], vcc, s[100:101]
	v_cndmask_b32_e64 v222, 0, 1, s[100:101]
	v_cmp_ne_u32_e64 s[100:101], 0, v222
	v_cndmask_b32_e64 v36, 0, 1, s[6:7]
.Ltk1_join:
	s_or_b64 s[20:21], s[12:13], s[20:21]
	s_or_b64 s[20:21], s[100:101], s[20:21]
	s_and_saveexec_b64 s[14:15], s[8:9]
	s_cbranch_execz .Ltk1_nowr
	s_add_i32 s25, s81, s19
	v_mov_b32_e32 v38, s25
	v_mov_b64_e32 v[40:41], s[12:13]
	ds_write_b64 v38, v[40:41]
	v_mov_b64_e32 v[224:225], s[100:101]
	ds_write_b64 v38, v[224:225] offset:8
.Ltk1_nowr:
	s_or_b64 exec, exec, s[14:15]
	s_add_i32 s19, s19, 16
	s_cmp_lg_u32 s19, 64
	v_add_u32_e32 v37, 0x200, v37
	s_cbranch_scc1 .LBB0_547
	s_branch .LBB0_553
.Ltk1_cold:
	v_cndmask_b32_e64 v36, 0, 1, s[6:7]
	v_cmp_ne_u32_e64 s[12:13], 0, v36
	s_mov_b64 s[100:101], s[12:13]
	s_branch .Ltk1_join

.LBB0_619:
	s_and_b64 vcc, exec, s[22:23]
	s_cbranch_vccz .Ltk2_cold
	ds_read_b32 v2, v34
	ds_read_b32 v222, v34 offset:256
	s_waitcnt lgkmcnt(0)
	v_max_f32_e32 v2, v2, v2
	v_max_f32_e32 v2, 0, v2
	v_add_u32_e32 v2, 1, v2
	v_cndmask_b32_e64 v2, v251, v2, s[10:11]
	v_cndmask_b32_e64 v2, 0, v2, s[6:7]
	v_max_f32_e32 v222, v222, v222
	v_max_f32_e32 v222, 0, v222
	v_add_u32_e32 v222, 1, v222
	v_cndmask_b32_e64 v222, v251, v222, s[10:11]
	v_cndmask_b32_e64 v222, 0, v222, s[6:7]
	v_cmp_lt_u32_e32 vcc, s3, v2
	v_cmp_lt_u32_e64 s[100:101], s3, v222
	s_bcnt1_i32_b64 s74, vcc
	s_bcnt1_i32_b64 s100, s[100:101]
	s_cmp_gt_u32 s74, 15
	s_cselect_b32 s12, 2.0, 0
	s_cmp_gt_u32 s100, 15
	s_cselect_b32 s98, 2.0, 0
	s_or_b32 s13, s12, 0x20000000
	s_or_b32 s99, s98, 0x20000000
	v_cmp_le_u32_e32 vcc, s13, v2
	v_cmp_le_u32_e64 s[100:101], s99, v222
	s_bcnt1_i32_b64 s74, vcc
	s_bcnt1_i32_b64 s100, s[100:101]
	s_cmp_gt_u32 s74, 15
	s_cselect_b32 s12, s13, s12
	s_cmp_gt_u32 s100, 15
	s_cselect_b32 s98, s99, s98
	s_or_b32 s13, s12, 0x10000000
	s_or_b32 s99, s98, 0x10000000
	v_cmp_le_u32_e32 vcc, s13, v2
	v_cmp_le_u32_e64 s[100:101], s99, v222
	s_bcnt1_i32_b64 s74, vcc
	s_bcnt1_i32_b64 s100, s[100:101]
	s_cmp_gt_u32 s74, 15
	s_cselect_b32 s12, s13, s12
	s_cmp_gt_u32 s100, 15
	s_cselect_b32 s98, s99, s98
	s_or_b32 s13, s12, 0x8000000
	s_or_b32 s99, s98, 0x8000000
	v_cmp_le_u32_e32 vcc, s13, v2
	v_cmp_le_u32_e64 s[100:101], s99, v222
	s_bcnt1_i32_b64 s74, vcc
	s_bcnt1_i32_b64 s100, s[100:101]
	s_cmp_gt_u32 s74, 15
	s_cselect_b32 s12, s13, s12
	s_cmp_gt_u32 s100, 15
	s_cselect_b32 s98, s99, s98
	s_or_b32 s13, s12, 0x4000000
	s_or_b32 s99, s98, 0x4000000
	v_cmp_le_u32_e32 vcc, s13, v2
	v_cmp_le_u32_e64 s[100:101], s99, v222
	s_bcnt1_i32_b64 s74, vcc
	s_bcnt1_i32_b64 s100, s[100:101]
	s_cmp_gt_u32 s74, 15
	s_cselect_b32 s12, s13, s12
	s_cmp_gt_u32 s100, 15
	s_cselect_b32 s98, s99, s98
	s_or_b32 s13, s12, 0x2000000
	s_or_b32 s99, s98, 0x2000000
	v_cmp_le_u32_e32 vcc, s13, v2
	v_cmp_le_u32_e64 s[100:101], s99, v222
	s_bcnt1_i32_b64 s74, vcc
	s_bcnt1_i32_b64 s100, s[100:101]
	s_cmp_gt_u32 s74, 15
	s_cselect_b32 s12, s13, s12
	s_cmp_gt_u32 s100, 15
	s_cselect_b32 s98, s99, s98
	s_or_b32 s13, s12, 0x1000000
	s_or_b32 s99, s98, 0x1000000
	v_cmp_le_u32_e32 vcc, s13, v2
	v_cmp_le_u32_e64 s[100:101], s99, v222
	s_bcnt1_i32_b64 s74, vcc
	s_bcnt1_i32_b64 s100, s[100:101]
	s_cmp_gt_u32 s74, 15
	s_cselect_b32 s12, s13, s12
	s_cmp_gt_u32 s100, 15
	s_cselect_b32 s98, s99, s98
	s_or_b32 s13, s12, 0x800000
	s_or_b32 s99, s98, 0x800000
	v_cmp_le_u32_e32 vcc, s13, v2
	v_cmp_le_u32_e64 s[100:101], s99, v222
	s_bcnt1_i32_b64 s74, vcc
	s_bcnt1_i32_b64 s100, s[100:101]
	s_cmp_gt_u32 s74, 15
	s_cselect_b32 s12, s13, s12
	s_cmp_gt_u32 s100, 15
	s_cselect_b32 s98, s99, s98
	s_or_b32 s13, s12, 0x400000
	s_or_b32 s99, s98, 0x400000
	v_cmp_le_u32_e32 vcc, s13, v2
	v_cmp_le_u32_e64 s[100:101], s99, v222
	s_bcnt1_i32_b64 s74, vcc
	s_bcnt1_i32_b64 s100, s[100:101]
	s_cmp_gt_u32 s74, 15
	s_cselect_b32 s12, s13, s12
	s_cmp_gt_u32 s100, 15
	s_cselect_b32 s98, s99, s98
	s_or_b32 s13, s12, 0x200000
	s_or_b32 s99, s98, 0x200000
	v_cmp_le_u32_e32 vcc, s13, v2
	v_cmp_le_u32_e64 s[100:101], s99, v222
	s_bcnt1_i32_b64 s74, vcc
	s_bcnt1_i32_b64 s100, s[100:101]
	s_cmp_gt_u32 s74, 15
	s_cselect_b32 s12, s13, s12
	s_cmp_gt_u32 s100, 15
	s_cselect_b32 s98, s99, s98
	s_or_b32 s13, s12, 0x100000
	s_or_b32 s99, s98, 0x100000
	v_cmp_le_u32_e32 vcc, s13, v2
	v_cmp_le_u32_e64 s[100:101], s99, v222
	s_bcnt1_i32_b64 s74, vcc
	s_bcnt1_i32_b64 s100, s[100:101]
	s_cmp_gt_u32 s74, 15
	s_cselect_b32 s12, s13, s12
	s_cmp_gt_u32 s100, 15
	s_cselect_b32 s98, s99, s98
	s_or_b32 s13, s12, 0x80000
	s_or_b32 s99, s98, 0x80000
	v_cmp_le_u32_e32 vcc, s13, v2
	v_cmp_le_u32_e64 s[100:101], s99, v222
	s_bcnt1_i32_b64 s74, vcc
	s_bcnt1_i32_b64 s100, s[100:101]
	s_cmp_gt_u32 s74, 15
	s_cselect_b32 s12, s13, s12
	s_cmp_gt_u32 s100, 15
	s_cselect_b32 s98, s99, s98
	s_or_b32 s13, s12, 0x40000
	s_or_b32 s99, s98, 0x40000
	v_cmp_le_u32_e32 vcc, s13, v2
	v_cmp_le_u32_e64 s[100:101], s99, v222
	s_bcnt1_i32_b64 s74, vcc
	s_bcnt1_i32_b64 s100, s[100:101]
	s_cmp_gt_u32 s74, 15
	s_cselect_b32 s12, s13, s12
	s_cmp_gt_u32 s100, 15
	s_cselect_b32 s98, s99, s98
	s_or_b32 s13, s12, 0x20000
	s_or_b32 s99, s98, 0x20000
	v_cmp_le_u32_e32 vcc, s13, v2
	v_cmp_le_u32_e64 s[100:101], s99, v222
	s_bcnt1_i32_b64 s74, vcc
	s_bcnt1_i32_b64 s100, s[100:101]
	s_cmp_gt_u32 s74, 15
	s_cselect_b32 s12, s13, s12
	s_cmp_gt_u32 s100, 15
	s_cselect_b32 s98, s99, s98
	s_or_b32 s13, s12, 0x10000
	s_or_b32 s99, s98, 0x10000
	v_cmp_le_u32_e32 vcc, s13, v2
	v_cmp_le_u32_e64 s[100:101], s99, v222
	s_bcnt1_i32_b64 s74, vcc
	s_bcnt1_i32_b64 s100, s[100:101]
	s_cmp_gt_u32 s74, 15
	s_cselect_b32 s12, s13, s12
	s_cmp_gt_u32 s100, 15
	s_cselect_b32 s98, s99, s98
	s_or_b32 s13, s12, 0x8000
	s_or_b32 s99, s98, 0x8000
	v_cmp_le_u32_e32 vcc, s13, v2
	v_cmp_le_u32_e64 s[100:101], s99, v222
	s_bcnt1_i32_b64 s74, vcc
	s_bcnt1_i32_b64 s100, s[100:101]
	s_cmp_gt_u32 s74, 15
	s_cselect_b32 s12, s13, s12
	s_cmp_gt_u32 s100, 15
	s_cselect_b32 s98, s99, s98
	s_or_b32 s13, s12, 0x4000
	s_or_b32 s99, s98, 0x4000
	v_cmp_le_u32_e32 vcc, s13, v2
	v_cmp_le_u32_e64 s[100:101], s99, v222
	s_bcnt1_i32_b64 s74, vcc
	s_bcnt1_i32_b64 s100, s[100:101]
	s_cmp_gt_u32 s74, 15
	s_cselect_b32 s12, s13, s12
	s_cmp_gt_u32 s100, 15
	s_cselect_b32 s98, s99, s98
	s_or_b32 s13, s12, 0x2000
	s_or_b32 s99, s98, 0x2000
	v_cmp_le_u32_e32 vcc, s13, v2
	v_cmp_le_u32_e64 s[100:101], s99, v222
	s_bcnt1_i32_b64 s74, vcc
	s_bcnt1_i32_b64 s100, s[100:101]
	s_cmp_gt_u32 s74, 15
	s_cselect_b32 s12, s13, s12
	s_cmp_gt_u32 s100, 15
	s_cselect_b32 s98, s99, s98
	s_or_b32 s13, s12, 0x1000
	s_or_b32 s99, s98, 0x1000
	v_cmp_le_u32_e32 vcc, s13, v2
	v_cmp_le_u32_e64 s[100:101], s99, v222
	s_bcnt1_i32_b64 s74, vcc
	s_bcnt1_i32_b64 s100, s[100:101]
	s_cmp_gt_u32 s74, 15
	s_cselect_b32 s12, s13, s12
	s_cmp_gt_u32 s100, 15
	s_cselect_b32 s98, s99, s98
	s_or_b32 s13, s12, 0x800
	s_or_b32 s99, s98, 0x800
	v_cmp_le_u32_e32 vcc, s13, v2
	v_cmp_le_u32_e64 s[100:101], s99, v222
	s_bcnt1_i32_b64 s74, vcc
	s_bcnt1_i32_b64 s100, s[100:101]
	s_cmp_gt_u32 s74, 15
	s_cselect_b32 s12, s13, s12
	s_cmp_gt_u32 s100, 15
	s_cselect_b32 s98, s99, s98
	s_or_b32 s13, s12, 0x400
	s_or_b32 s99, s98, 0x400
	v_cmp_le_u32_e32 vcc, s13, v2
	v_cmp_le_u32_e64 s[100:101], s99, v222
	s_bcnt1_i32_b64 s74, vcc
	s_bcnt1_i32_b64 s100, s[100:101]
	s_cmp_gt_u32 s74, 15
	s_cselect_b32 s12, s13, s12
	s_cmp_gt_u32 s100, 15
	s_cselect_b32 s98, s99, s98
	s_or_b32 s13, s12, 0x200
	s_or_b32 s99, s98, 0x200
	v_cmp_le_u32_e32 vcc, s13, v2
	v_cmp_le_u32_e64 s[100:101], s99, v222
	s_bcnt1_i32_b64 s74, vcc
	s_bcnt1_i32_b64 s100, s[100:101]
	s_cmp_gt_u32 s74, 15
	s_cselect_b32 s12, s13, s12
	s_cmp_gt_u32 s100, 15
	s_cselect_b32 s98, s99, s98
	s_or_b32 s13, s12, 0x100
	s_or_b32 s99, s98, 0x100
	v_cmp_le_u32_e32 vcc, s13, v2
	v_cmp_le_u32_e64 s[100:101], s99, v222
	s_bcnt1_i32_b64 s74, vcc
	s_bcnt1_i32_b64 s100, s[100:101]
	s_cmp_gt_u32 s74, 15
	s_cselect_b32 s12, s13, s12
	s_cmp_gt_u32 s100, 15
	s_cselect_b32 s98, s99, s98
	s_or_b32 s13, s12, 0x80
	s_or_b32 s99, s98, 0x80
	v_cmp_le_u32_e32 vcc, s13, v2
	v_cmp_le_u32_e64 s[100:101], s99, v222
	s_bcnt1_i32_b64 s74, vcc
	s_bcnt1_i32_b64 s100, s[100:101]
	s_cmp_gt_u32 s74, 15
	s_cselect_b32 s12, s13, s12
	s_cmp_gt_u32 s100, 15
	s_cselect_b32 s98, s99, s98
	s_or_b32 s13, s12, 64
	s_or_b32 s99, s98, 64
	v_cmp_le_u32_e32 vcc, s13, v2
	v_cmp_le_u32_e64 s[100:101], s99, v222
	s_bcnt1_i32_b64 s74, vcc
	s_bcnt1_i32_b64 s100, s[100:101]
	s_cmp_gt_u32 s74, 15
	s_cselect_b32 s12, s13, s12
	s_cmp_gt_u32 s100, 15
	s_cselect_b32 s98, s99, s98
	s_or_b32 s13, s12, 32
	s_or_b32 s99, s98, 32
	v_cmp_le_u32_e32 vcc, s13, v2
	v_cmp_le_u32_e64 s[100:101], s99, v222
	s_bcnt1_i32_b64 s74, vcc
	s_bcnt1_i32_b64 s100, s[100:101]
	s_cmp_gt_u32 s74, 15
	s_cselect_b32 s12, s13, s12
	s_cmp_gt_u32 s100, 15
	s_cselect_b32 s98, s99, s98
	s_or_b32 s13, s12, 16
	s_or_b32 s99, s98, 16
	v_cmp_le_u32_e32 vcc, s13, v2
	v_cmp_le_u32_e64 s[100:101], s99, v222
	s_bcnt1_i32_b64 s74, vcc
	s_bcnt1_i32_b64 s100, s[100:101]
	s_cmp_gt_u32 s74, 15
	s_cselect_b32 s12, s13, s12
	s_cmp_gt_u32 s100, 15
	s_cselect_b32 s98, s99, s98
	s_or_b32 s13, s12, 8
	s_or_b32 s99, s98, 8
	v_cmp_le_u32_e32 vcc, s13, v2
	v_cmp_le_u32_e64 s[100:101], s99, v222
	s_bcnt1_i32_b64 s74, vcc
	s_bcnt1_i32_b64 s100, s[100:101]
	s_cmp_gt_u32 s74, 15
	s_cselect_b32 s12, s13, s12
	s_cmp_gt_u32 s100, 15
	s_cselect_b32 s98, s99, s98
	s_or_b32 s13, s12, 4
	s_or_b32 s99, s98, 4
	v_cmp_le_u32_e32 vcc, s13, v2
	v_cmp_le_u32_e64 s[100:101], s99, v222
	s_bcnt1_i32_b64 s74, vcc
	s_bcnt1_i32_b64 s100, s[100:101]
	s_cmp_gt_u32 s74, 15
	s_cselect_b32 s12, s13, s12
	s_cmp_gt_u32 s100, 15
	s_cselect_b32 s98, s99, s98
	s_or_b32 s13, s12, 2
	s_or_b32 s99, s98, 2
	v_cmp_le_u32_e32 vcc, s13, v2
	v_cmp_le_u32_e64 s[100:101], s99, v222
	s_bcnt1_i32_b64 s74, vcc
	s_bcnt1_i32_b64 s100, s[100:101]
	s_cmp_gt_u32 s74, 15
	s_cselect_b32 s12, s13, s12
	s_cmp_gt_u32 s100, 15
	s_cselect_b32 s98, s99, s98
	s_or_b32 s13, s12, 1
	s_or_b32 s99, s98, 1
	v_cmp_le_u32_e32 vcc, s13, v2
	v_cmp_le_u32_e64 s[100:101], s99, v222
	s_bcnt1_i32_b64 s74, vcc
	s_bcnt1_i32_b64 s100, s[100:101]
	s_cmp_gt_u32 s74, 15
	s_cselect_b32 s4, s13, s12
	s_cmp_gt_u32 s100, 15
	s_cselect_b32 s98, s99, s98
	v_cmp_lt_u32_e32 vcc, s4, v2
	v_cmp_eq_u32_e64 s[4:5], s4, v2
	s_bcnt1_i32_b64 s12, vcc
	s_sub_i32 s12, 16, s12
	v_and_b32_e32 v2, s4, v0
	v_and_b32_e32 v3, s5, v35
	v_bcnt_u32_b32 v2, v2, 0
	v_bcnt_u32_b32 v2, v3, v2
	v_cmp_gt_i32_e64 s[12:13], s12, v2
	s_and_b64 s[4:5], s[4:5], s[12:13]
	s_or_b64 s[4:5], vcc, s[4:5]
	v_cndmask_b32_e64 v2, 0, 1, s[4:5]
	v_cmp_ne_u32_e64 s[4:5], 0, v2
	v_cmp_lt_u32_e32 vcc, s98, v222
	v_cmp_eq_u32_e64 s[100:101], s98, v222
	s_bcnt1_i32_b64 s99, vcc
	s_sub_i32 s99, 16, s99
	v_and_b32_e32 v222, s100, v0
	v_and_b32_e32 v223, s101, v35
	v_bcnt_u32_b32 v222, v222, 0
	v_bcnt_u32_b32 v222, v223, v222
	v_cmp_gt_i32_e64 s[12:13], s99, v222
	s_and_b64 s[100:101], s[100:101], s[12:13]
	s_or_b64 s[100:101], vcc, s[100:101]
	v_cndmask_b32_e64 v222, 0, 1, s[100:101]
	v_cmp_ne_u32_e64 s[100:101], 0, v222
.Ltk2_join:
	s_or_b64 s[20:21], s[4:5], s[20:21]
	s_or_b64 s[20:21], s[100:101], s[20:21]
	s_and_saveexec_b64 s[12:13], s[8:9]
	s_cbranch_execz .Ltk2_nowr
	s_add_i32 s15, s81, s14
	v_mov_b32_e32 v2, s15
	v_mov_b64_e32 v[4:5], s[4:5]
	ds_write_b64 v2, v[4:5]
	v_mov_b64_e32 v[224:225], s[100:101]
	ds_write_b64 v2, v[224:225] offset:8
.Ltk2_nowr:
	s_or_b64 exec, exec, s[12:13]
	s_add_i32 s14, s14, 16
	s_cmp_lg_u32 s14, 64
	v_add_u32_e32 v34, 0x200, v34
	s_cbranch_scc1 .LBB0_619
	s_branch .LBB0_625
.Ltk2_cold:
	v_cndmask_b32_e64 v36, 0, 1, s[6:7]
	v_cmp_ne_u32_e64 s[4:5], 0, v36
	s_mov_b64 s[100:101], s[4:5]
	s_branch .Ltk2_join
